# v3 + six micro-edits stacked: K-loop SALU hoist, LoRA dead-half MFMA skip, barrier TOPGEN spin, scan chain read re-pairing (-12 v_mov), scan-C bit-trick pack -> v_cvt_pk_bf16_f32, scan-C LDS address a
# speedup vs baseline: 1.0054x; 1.0054x over previous
.LBB0_1172:
	v_lshl_add_u64 v[76:77], v[2:3], 0, s[68:69]
	v_add_u32_e32 v85, 0, v5
	v_add_co_u32_e32 v84, vcc, 0x38100000, v76
	v_add_u32_e32 v82, 0, v83
	v_ashrrev_i32_e32 v73, 31, v72
	v_add_u32_e32 v99, 0x21e00, v85
	v_addc_co_u32_e32 v85, vcc, 0, v77, vcc
	s_mov_b32 s0, 0x1ba00000
	v_add_u32_e32 v86, 0x19c00, v82
	v_lshlrev_b64 v[88:89], 12, v[72:73]
	v_add_co_u32_e32 v90, vcc, 0x34000000, v76
	v_add_co_u32_e64 v92, s[34:35], s0, v76
	ds_read_u16 v107, v86
	ds_read_u16 v108, v86 offset:512
	ds_read_u16 v109, v86 offset:768
	ds_read_u16 v95, v86 offset:1024
	ds_read_u16 v110, v86 offset:1536
	ds_read_u16 v111, v86 offset:1792
	ds_read_u16 v112, v86 offset:1280
	ds_read_u16 v113, v86 offset:256
	v_lshl_or_b32 v88, v124, 1, v88
	v_addc_co_u32_e32 v91, vcc, 0, v77, vcc
	v_addc_co_u32_e64 v93, s[34:35], 0, v77, s[34:35]
	ds_read_b32 v94, v99
	ds_read_u16 v73, v86 offset:64
	ds_read_u16 v114, v86 offset:576
	ds_read_u16 v115, v86 offset:832
	ds_read_u16 v116, v86 offset:1088
	ds_read_u16 v117, v86 offset:1600
	ds_read_u16 v133, v86 offset:1344
	ds_read_u16 v140, v86 offset:320
	ds_read_u16 v141, v86 offset:1856
	ds_read_b32 v82, v99 offset:128
	s_waitcnt vmcnt(7)
	s_nop 1
	v_mov_b32_e32 v84, v192
	v_mov_b32_e32 v85, v193
	v_mov_b32_e32 v86, v194
	v_mov_b32_e32 v87, v195
	v_lshl_add_u64 v[96:97], s[2:3], 0, v[88:89]
	v_lshl_add_u64 v[98:99], s[4:5], 0, v[88:89]
	v_lshl_add_u64 v[76:77], s[6:7], 0, v[88:89]
	s_waitcnt vmcnt(6)
	s_nop 1
	v_mov_b32_e32 v88, v196
	v_mov_b32_e32 v89, v197
	v_mov_b32_e32 v90, v198
	v_mov_b32_e32 v91, v199
	s_waitcnt lgkmcnt(14)
	v_lshlrev_b32_e32 v100, 16, v107
	v_lshlrev_b32_e32 v101, 16, v108
	s_waitcnt lgkmcnt(10)
	v_lshlrev_b32_e32 v102, 16, v113
	s_waitcnt lgkmcnt(8)
	v_lshlrev_b32_e32 v108, 16, v73
	v_add_f32_e32 v73, 0, v100
	v_add_f32_e32 v73, v73, v102
	v_lshlrev_b32_e32 v103, 16, v109
	v_add_f32_e32 v73, v73, v101
	v_lshlrev_b32_e32 v104, 16, v95
	v_add_f32_e32 v73, v73, v103
	v_lshlrev_b32_e32 v106, 16, v112
	v_add_f32_e32 v73, v73, v104
	v_lshlrev_b32_e32 v105, 16, v110
	v_add_f32_e32 v73, v73, v106
	v_lshlrev_b32_e32 v107, 16, v111
	v_add_f32_e32 v73, v73, v105
	v_add_f32_e32 v73, v73, v107
	s_waitcnt lgkmcnt(5)
	v_lshlrev_b32_e32 v112, 16, v116
	s_waitcnt lgkmcnt(4)
	v_lshlrev_b32_e32 v113, 16, v117
	v_add_f32_dpp v73, v73, v73 quad_perm:[1,0,3,2] row_mask:0xf bank_mask:0xf bound_ctrl:1
	s_waitcnt lgkmcnt(2)
	v_lshlrev_b32_e32 v110, 16, v140
	v_add_f32_e32 v95, 0, v108
	v_add_f32_dpp v73, v73, v73 quad_perm:[2,3,0,1] row_mask:0xf bank_mask:0xf bound_ctrl:1
	v_lshlrev_b32_e32 v109, 16, v114
	v_add_f32_e32 v95, v95, v110
	v_add_f32_dpp v73, v73, v73 row_half_mirror row_mask:0xf bank_mask:0xf bound_ctrl:1
	v_mul_f32_e32 v116, 0x3c800000, v73
	v_pk_add_f32 v[100:101], v[100:101], v[116:117] op_sel_hi:[1,0] neg_lo:[0,1] neg_hi:[0,1]
	v_pk_add_f32 v[102:103], v[102:103], v[116:117] op_sel_hi:[1,0] neg_lo:[0,1] neg_hi:[0,1]
	v_pk_add_f32 v[104:105], v[104:105], v[116:117] op_sel_hi:[1,0] neg_lo:[0,1] neg_hi:[0,1]
	v_pk_add_f32 v[106:107], v[106:107], v[116:117] op_sel_hi:[1,0] neg_lo:[0,1] neg_hi:[0,1]
	v_mov_b32_e32 v116, v103
	v_mov_b32_e32 v117, v101
	v_mul_f32_e32 v73, v100, v100
	v_pk_mul_f32 v[116:117], v[116:117], v[116:117]
	v_fmac_f32_e32 v73, v102, v102
	v_mov_b32_e32 v142, v106
	v_mov_b32_e32 v143, v104
	v_add_f32_e32 v73, v117, v73
	v_pk_mul_f32 v[142:143], v[142:143], v[142:143]
	v_add_f32_e32 v73, v116, v73
	v_mov_b32_e32 v144, v107
	v_mov_b32_e32 v145, v105
	v_add_f32_e32 v73, v143, v73
	v_pk_mul_f32 v[144:145], v[144:145], v[144:145]
	v_add_f32_e32 v73, v142, v73
	v_add_f32_e32 v73, v145, v73
	v_add_f32_e32 v73, v144, v73
	v_lshlrev_b32_e32 v111, 16, v115
	v_add_f32_e32 v95, v95, v109
	v_add_f32_dpp v73, v73, v73 quad_perm:[1,0,3,2] row_mask:0xf bank_mask:0xf bound_ctrl:1
	v_add_f32_e32 v95, v95, v111
	v_lshlrev_b32_e32 v114, 16, v133
	v_add_f32_dpp v73, v73, v73 quad_perm:[2,3,0,1] row_mask:0xf bank_mask:0xf bound_ctrl:1
	v_add_f32_e32 v95, v95, v112
	v_add_f32_e32 v95, v95, v114
	v_add_f32_dpp v73, v73, v73 row_half_mirror row_mask:0xf bank_mask:0xf bound_ctrl:1
	v_fmamk_f32 v73, v73, 0x3c800000, v184
	v_rsq_f32_e32 v116, v73
	s_waitcnt lgkmcnt(1)
	v_lshlrev_b32_e32 v115, 16, v141
	v_add_f32_e32 v95, v95, v113
	v_add_f32_e32 v95, v95, v115
	v_pk_mul_f32 v[100:101], v[100:101], v[116:117] op_sel_hi:[1,0]
	v_pk_mul_f32 v[102:103], v[102:103], v[116:117] op_sel_hi:[1,0]
	v_add_f32_dpp v95, v95, v95 quad_perm:[1,0,3,2] row_mask:0xf bank_mask:0xf bound_ctrl:1
	v_pk_mul_f32 v[104:105], v[104:105], v[116:117] op_sel_hi:[1,0]
	v_pk_mul_f32 v[106:107], v[106:107], v[116:117] op_sel_hi:[1,0]
	v_add_f32_dpp v95, v95, v95 quad_perm:[2,3,0,1] row_mask:0xf bank_mask:0xf bound_ctrl:1
	v_pk_fma_f32 v[100:101], v[66:67], v[100:101], v[62:63]
	v_pk_fma_f32 v[102:103], v[80:81], v[102:103], v[78:79]
	v_add_f32_dpp v95, v95, v95 row_half_mirror row_mask:0xf bank_mask:0xf bound_ctrl:1
	v_pk_fma_f32 v[104:105], v[70:71], v[104:105], v[74:75]
	v_pk_fma_f32 v[106:107], v[68:69], v[106:107], v[64:65]
	v_mul_f32_e32 v140, 0x3c800000, v95
	v_add_u32_e32 v83, 0x80, v83
	v_lshlrev_b32_e32 v117, 16, v85
	v_lshlrev_b32_e32 v116, 16, v84
	v_and_b32_e32 v85, 0xffff0000, v85
	v_and_b32_e32 v84, 0xffff0000, v84
	v_lshlrev_b32_e32 v145, 16, v89
	v_lshlrev_b32_e32 v144, 16, v88
	v_and_b32_e32 v89, 0xffff0000, v89
	v_and_b32_e32 v88, 0xffff0000, v88
	v_lshlrev_b32_e32 v147, 16, v91
	v_lshlrev_b32_e32 v146, 16, v90
	v_and_b32_e32 v91, 0xffff0000, v91
	v_and_b32_e32 v90, 0xffff0000, v90
	v_lshlrev_b32_e32 v143, 16, v87
	v_lshlrev_b32_e32 v142, 16, v86
	v_and_b32_e32 v87, 0xffff0000, v87
	v_and_b32_e32 v86, 0xffff0000, v86
	v_pk_fma_f32 v[100:101], v[94:95], v[144:145], v[100:101] op_sel_hi:[0,1,1]
	v_pk_fma_f32 v[88:89], v[94:95], v[88:89], v[102:103] op_sel_hi:[0,1,1]
	v_pk_fma_f32 v[102:103], v[94:95], v[146:147], v[104:105] op_sel_hi:[0,1,1]
	v_pk_fma_f32 v[90:91], v[94:95], v[90:91], v[106:107] op_sel_hi:[0,1,1]
	v_pk_mul_f32 v[94:95], v[100:101], v[116:117]
	v_pk_mul_f32 v[84:85], v[88:89], v[84:85]
	v_pk_mul_f32 v[88:89], v[102:103], v[142:143]
	v_pk_mul_f32 v[86:87], v[90:91], v[86:87]
	v_cvt_pk_bf16_f32 v87, v89, v87
	v_cvt_pk_bf16_f32 v86, v88, v86
	v_cvt_pk_bf16_f32 v85, v95, v85
	v_cvt_pk_bf16_f32 v84, v94, v84
	global_store_dwordx4 v[92:93], v[84:87], off
	s_waitcnt vmcnt(6)
	s_nop 1
	v_mov_b32_e32 v84, v200
	v_mov_b32_e32 v85, v201
	v_mov_b32_e32 v86, v202
	v_mov_b32_e32 v87, v203
	s_nop 0
	s_waitcnt vmcnt(5)
	s_nop 1
	v_mov_b32_e32 v88, v204
	v_mov_b32_e32 v89, v205
	v_mov_b32_e32 v90, v206
	v_mov_b32_e32 v91, v207
	v_pk_add_f32 v[92:93], v[108:109], v[140:141] op_sel_hi:[1,0] neg_lo:[0,1] neg_hi:[0,1]
	v_pk_add_f32 v[94:95], v[110:111], v[140:141] op_sel_hi:[1,0] neg_lo:[0,1] neg_hi:[0,1]
	v_mov_b32_e32 v101, v93
	v_mov_b32_e32 v100, v95
	v_mul_f32_e32 v73, v92, v92
	v_pk_add_f32 v[96:97], v[112:113], v[140:141] op_sel_hi:[1,0] neg_lo:[0,1] neg_hi:[0,1]
	v_pk_add_f32 v[98:99], v[114:115], v[140:141] op_sel_hi:[1,0] neg_lo:[0,1] neg_hi:[0,1]
	v_pk_mul_f32 v[100:101], v[100:101], v[100:101]
	v_fmac_f32_e32 v73, v94, v94
	v_mov_b32_e32 v102, v98
	v_mov_b32_e32 v103, v96
	v_add_f32_e32 v73, v101, v73
	v_pk_mul_f32 v[102:103], v[102:103], v[102:103]
	v_add_f32_e32 v73, v100, v73
	v_mov_b32_e32 v104, v99
	v_mov_b32_e32 v105, v97
	v_add_f32_e32 v73, v103, v73
	v_pk_mul_f32 v[104:105], v[104:105], v[104:105]
	v_add_f32_e32 v73, v102, v73
	v_add_f32_e32 v73, v105, v73
	v_add_f32_e32 v73, v104, v73
	s_add_u32 s68, s68, 0x40000
	s_addc_u32 s69, s69, 0
	v_add_f32_dpp v73, v73, v73 quad_perm:[1,0,3,2] row_mask:0xf bank_mask:0xf bound_ctrl:1
	v_add_u32_e32 v5, 0x100, v5
	v_add_u32_e32 v72, 64, v72
	v_add_f32_dpp v73, v73, v73 quad_perm:[2,3,0,1] row_mask:0xf bank_mask:0xf bound_ctrl:1
	s_cmp_lg_u32 s68, 0x80000
	v_lshlrev_b32_e32 v105, 16, v87
	v_add_f32_dpp v73, v73, v73 row_half_mirror row_mask:0xf bank_mask:0xf bound_ctrl:1
	v_fmamk_f32 v73, v73, 0x3c800000, v184
	v_rsq_f32_e32 v100, v73
	v_lshlrev_b32_e32 v104, 16, v86
	v_and_b32_e32 v87, 0xffff0000, v87
	v_and_b32_e32 v86, 0xffff0000, v86
	v_pk_mul_f32 v[92:93], v[92:93], v[100:101] op_sel_hi:[1,0]
	v_pk_mul_f32 v[94:95], v[94:95], v[100:101] op_sel_hi:[1,0]
	v_pk_mul_f32 v[96:97], v[96:97], v[100:101] op_sel_hi:[1,0]
	v_pk_mul_f32 v[98:99], v[98:99], v[100:101] op_sel_hi:[1,0]
	v_pk_fma_f32 v[92:93], v[66:67], v[92:93], v[62:63]
	v_pk_fma_f32 v[94:95], v[80:81], v[94:95], v[78:79]
	v_pk_fma_f32 v[96:97], v[70:71], v[96:97], v[74:75]
	v_pk_fma_f32 v[98:99], v[68:69], v[98:99], v[64:65]
	v_lshlrev_b32_e32 v101, 16, v85
	v_lshlrev_b32_e32 v100, 16, v84
	v_and_b32_e32 v85, 0xffff0000, v85
	v_and_b32_e32 v84, 0xffff0000, v84
	v_lshlrev_b32_e32 v103, 16, v89
	v_lshlrev_b32_e32 v102, 16, v88
	v_and_b32_e32 v89, 0xffff0000, v89
	v_and_b32_e32 v88, 0xffff0000, v88
	v_lshlrev_b32_e32 v107, 16, v91
	v_lshlrev_b32_e32 v106, 16, v90
	v_and_b32_e32 v91, 0xffff0000, v91
	v_and_b32_e32 v90, 0xffff0000, v90
	s_waitcnt lgkmcnt(0)
	v_pk_fma_f32 v[92:93], v[82:83], v[100:101], v[92:93] op_sel_hi:[0,1,1]
	v_pk_fma_f32 v[84:85], v[82:83], v[84:85], v[94:95] op_sel_hi:[0,1,1]
	v_pk_fma_f32 v[94:95], v[82:83], v[104:105], v[96:97] op_sel_hi:[0,1,1]
	v_pk_fma_f32 v[86:87], v[82:83], v[86:87], v[98:99] op_sel_hi:[0,1,1]
	v_pk_mul_f32 v[92:93], v[92:93], v[102:103]
	v_pk_mul_f32 v[84:85], v[84:85], v[88:89]
	v_pk_mul_f32 v[88:89], v[94:95], v[106:107]
	v_pk_mul_f32 v[86:87], v[86:87], v[90:91]
	v_cvt_pk_bf16_f32 v87, v89, v87
	v_cvt_pk_bf16_f32 v86, v88, v86
	v_cvt_pk_bf16_f32 v85, v93, v85
	v_cvt_pk_bf16_f32 v84, v92, v84
	global_store_dwordx4 v[76:77], v[84:87], off
	s_nop 1
	v_lshl_add_u64 v[76:77], v[2:3], 0, s[68:69]
	v_add_u32_e32 v85, 0, v5
	v_add_co_u32_e32 v84, vcc, 0x38100000, v76
	v_add_u32_e32 v82, 0, v83
	v_ashrrev_i32_e32 v73, 31, v72
	v_add_u32_e32 v99, 0x21e00, v85
	v_addc_co_u32_e32 v85, vcc, 0, v77, vcc
	s_mov_b32 s0, 0x1ba00000
	v_add_u32_e32 v86, 0x19c00, v82
	v_lshlrev_b64 v[88:89], 12, v[72:73]
	v_add_co_u32_e32 v90, vcc, 0x34000000, v76
	v_add_co_u32_e64 v92, s[34:35], s0, v76
	ds_read_u16 v107, v86
	ds_read_u16 v108, v86 offset:512
	ds_read_u16 v109, v86 offset:768
	ds_read_u16 v95, v86 offset:1024
	ds_read_u16 v110, v86 offset:1536
	ds_read_u16 v111, v86 offset:1792
	ds_read_u16 v112, v86 offset:1280
	ds_read_u16 v113, v86 offset:256
	v_lshl_or_b32 v88, v124, 1, v88
	v_addc_co_u32_e32 v91, vcc, 0, v77, vcc
	v_addc_co_u32_e64 v93, s[34:35], 0, v77, s[34:35]
	ds_read_b32 v94, v99
	ds_read_u16 v73, v86 offset:64
	ds_read_u16 v114, v86 offset:576
	ds_read_u16 v115, v86 offset:832
	ds_read_u16 v116, v86 offset:1088
	ds_read_u16 v117, v86 offset:1600
	ds_read_u16 v133, v86 offset:1344
	ds_read_u16 v140, v86 offset:320
	ds_read_u16 v141, v86 offset:1856
	ds_read_b32 v82, v99 offset:128
	s_waitcnt vmcnt(5)
	s_nop 1
	v_mov_b32_e32 v84, v208
	v_mov_b32_e32 v85, v209
	v_mov_b32_e32 v86, v210
	v_mov_b32_e32 v87, v211
	v_lshl_add_u64 v[96:97], s[2:3], 0, v[88:89]
	v_lshl_add_u64 v[98:99], s[4:5], 0, v[88:89]
	v_lshl_add_u64 v[76:77], s[6:7], 0, v[88:89]
	s_waitcnt vmcnt(4)
	s_nop 1
	v_mov_b32_e32 v88, v212
	v_mov_b32_e32 v89, v213
	v_mov_b32_e32 v90, v214
	v_mov_b32_e32 v91, v215
	s_waitcnt lgkmcnt(14)
	v_lshlrev_b32_e32 v100, 16, v107
	v_lshlrev_b32_e32 v101, 16, v108
	s_waitcnt lgkmcnt(10)
	v_lshlrev_b32_e32 v102, 16, v113
	s_waitcnt lgkmcnt(8)
	v_lshlrev_b32_e32 v108, 16, v73
	v_add_f32_e32 v73, 0, v100
	v_add_f32_e32 v73, v73, v102
	v_lshlrev_b32_e32 v103, 16, v109
	v_add_f32_e32 v73, v73, v101
	v_lshlrev_b32_e32 v104, 16, v95
	v_add_f32_e32 v73, v73, v103
	v_lshlrev_b32_e32 v106, 16, v112
	v_add_f32_e32 v73, v73, v104
	v_lshlrev_b32_e32 v105, 16, v110
	v_add_f32_e32 v73, v73, v106
	v_lshlrev_b32_e32 v107, 16, v111
	v_add_f32_e32 v73, v73, v105
	v_add_f32_e32 v73, v73, v107
	s_waitcnt lgkmcnt(5)
	v_lshlrev_b32_e32 v112, 16, v116
	s_waitcnt lgkmcnt(4)
	v_lshlrev_b32_e32 v113, 16, v117
	v_add_f32_dpp v73, v73, v73 quad_perm:[1,0,3,2] row_mask:0xf bank_mask:0xf bound_ctrl:1
	s_waitcnt lgkmcnt(2)
	v_lshlrev_b32_e32 v110, 16, v140
	v_add_f32_e32 v95, 0, v108
	v_add_f32_dpp v73, v73, v73 quad_perm:[2,3,0,1] row_mask:0xf bank_mask:0xf bound_ctrl:1
	v_lshlrev_b32_e32 v109, 16, v114
	v_add_f32_e32 v95, v95, v110
	v_add_f32_dpp v73, v73, v73 row_half_mirror row_mask:0xf bank_mask:0xf bound_ctrl:1
	v_mul_f32_e32 v116, 0x3c800000, v73
	v_pk_add_f32 v[100:101], v[100:101], v[116:117] op_sel_hi:[1,0] neg_lo:[0,1] neg_hi:[0,1]
	v_pk_add_f32 v[102:103], v[102:103], v[116:117] op_sel_hi:[1,0] neg_lo:[0,1] neg_hi:[0,1]
	v_pk_add_f32 v[104:105], v[104:105], v[116:117] op_sel_hi:[1,0] neg_lo:[0,1] neg_hi:[0,1]
	v_pk_add_f32 v[106:107], v[106:107], v[116:117] op_sel_hi:[1,0] neg_lo:[0,1] neg_hi:[0,1]
	v_mov_b32_e32 v116, v103
	v_mov_b32_e32 v117, v101
	v_mul_f32_e32 v73, v100, v100
	v_pk_mul_f32 v[116:117], v[116:117], v[116:117]
	v_fmac_f32_e32 v73, v102, v102
	v_mov_b32_e32 v142, v106
	v_mov_b32_e32 v143, v104
	v_add_f32_e32 v73, v117, v73
	v_pk_mul_f32 v[142:143], v[142:143], v[142:143]
	v_add_f32_e32 v73, v116, v73
	v_mov_b32_e32 v144, v107
	v_mov_b32_e32 v145, v105
	v_add_f32_e32 v73, v143, v73
	v_pk_mul_f32 v[144:145], v[144:145], v[144:145]
	v_add_f32_e32 v73, v142, v73
	v_add_f32_e32 v73, v145, v73
	v_add_f32_e32 v73, v144, v73
	v_lshlrev_b32_e32 v111, 16, v115
	v_add_f32_e32 v95, v95, v109
	v_add_f32_dpp v73, v73, v73 quad_perm:[1,0,3,2] row_mask:0xf bank_mask:0xf bound_ctrl:1
	v_add_f32_e32 v95, v95, v111
	v_lshlrev_b32_e32 v114, 16, v133
	v_add_f32_dpp v73, v73, v73 quad_perm:[2,3,0,1] row_mask:0xf bank_mask:0xf bound_ctrl:1
	v_add_f32_e32 v95, v95, v112
	v_add_f32_e32 v95, v95, v114
	v_add_f32_dpp v73, v73, v73 row_half_mirror row_mask:0xf bank_mask:0xf bound_ctrl:1
	v_fmamk_f32 v73, v73, 0x3c800000, v184
	v_rsq_f32_e32 v116, v73
	s_waitcnt lgkmcnt(1)
	v_lshlrev_b32_e32 v115, 16, v141
	v_add_f32_e32 v95, v95, v113
	v_add_f32_e32 v95, v95, v115
	v_pk_mul_f32 v[100:101], v[100:101], v[116:117] op_sel_hi:[1,0]
	v_pk_mul_f32 v[102:103], v[102:103], v[116:117] op_sel_hi:[1,0]
	v_add_f32_dpp v95, v95, v95 quad_perm:[1,0,3,2] row_mask:0xf bank_mask:0xf bound_ctrl:1
	v_pk_mul_f32 v[104:105], v[104:105], v[116:117] op_sel_hi:[1,0]
	v_pk_mul_f32 v[106:107], v[106:107], v[116:117] op_sel_hi:[1,0]
	v_add_f32_dpp v95, v95, v95 quad_perm:[2,3,0,1] row_mask:0xf bank_mask:0xf bound_ctrl:1
	v_pk_fma_f32 v[100:101], v[66:67], v[100:101], v[62:63]
	v_pk_fma_f32 v[102:103], v[80:81], v[102:103], v[78:79]
	v_add_f32_dpp v95, v95, v95 row_half_mirror row_mask:0xf bank_mask:0xf bound_ctrl:1
	v_pk_fma_f32 v[104:105], v[70:71], v[104:105], v[74:75]
	v_pk_fma_f32 v[106:107], v[68:69], v[106:107], v[64:65]
	v_mul_f32_e32 v140, 0x3c800000, v95
	v_add_u32_e32 v83, 0x80, v83
	v_lshlrev_b32_e32 v117, 16, v85
	v_lshlrev_b32_e32 v116, 16, v84
	v_and_b32_e32 v85, 0xffff0000, v85
	v_and_b32_e32 v84, 0xffff0000, v84
	v_lshlrev_b32_e32 v145, 16, v89
	v_lshlrev_b32_e32 v144, 16, v88
	v_and_b32_e32 v89, 0xffff0000, v89
	v_and_b32_e32 v88, 0xffff0000, v88
	v_lshlrev_b32_e32 v147, 16, v91
	v_lshlrev_b32_e32 v146, 16, v90
	v_and_b32_e32 v91, 0xffff0000, v91
	v_and_b32_e32 v90, 0xffff0000, v90
	v_lshlrev_b32_e32 v143, 16, v87
	v_lshlrev_b32_e32 v142, 16, v86
	v_and_b32_e32 v87, 0xffff0000, v87
	v_and_b32_e32 v86, 0xffff0000, v86
	v_pk_fma_f32 v[100:101], v[94:95], v[144:145], v[100:101] op_sel_hi:[0,1,1]
	v_pk_fma_f32 v[88:89], v[94:95], v[88:89], v[102:103] op_sel_hi:[0,1,1]
	v_pk_fma_f32 v[102:103], v[94:95], v[146:147], v[104:105] op_sel_hi:[0,1,1]
	v_pk_fma_f32 v[90:91], v[94:95], v[90:91], v[106:107] op_sel_hi:[0,1,1]
	v_pk_mul_f32 v[94:95], v[100:101], v[116:117]
	v_pk_mul_f32 v[84:85], v[88:89], v[84:85]
	v_pk_mul_f32 v[88:89], v[102:103], v[142:143]
	v_pk_mul_f32 v[86:87], v[90:91], v[86:87]
	v_cvt_pk_bf16_f32 v87, v89, v87
	v_cvt_pk_bf16_f32 v86, v88, v86
	v_cvt_pk_bf16_f32 v85, v95, v85
	v_cvt_pk_bf16_f32 v84, v94, v84
	global_store_dwordx4 v[92:93], v[84:87], off
	s_waitcnt vmcnt(4)
	s_nop 1
	v_mov_b32_e32 v84, v216
	v_mov_b32_e32 v85, v217
	v_mov_b32_e32 v86, v218
	v_mov_b32_e32 v87, v219
	s_nop 0
	s_waitcnt vmcnt(3)
	s_nop 1
	v_mov_b32_e32 v88, v220
	v_mov_b32_e32 v89, v221
	v_mov_b32_e32 v90, v222
	v_mov_b32_e32 v91, v223
	v_pk_add_f32 v[92:93], v[108:109], v[140:141] op_sel_hi:[1,0] neg_lo:[0,1] neg_hi:[0,1]
	v_pk_add_f32 v[94:95], v[110:111], v[140:141] op_sel_hi:[1,0] neg_lo:[0,1] neg_hi:[0,1]
	v_mov_b32_e32 v101, v93
	v_mov_b32_e32 v100, v95
	v_mul_f32_e32 v73, v92, v92
	v_pk_add_f32 v[96:97], v[112:113], v[140:141] op_sel_hi:[1,0] neg_lo:[0,1] neg_hi:[0,1]
	v_pk_add_f32 v[98:99], v[114:115], v[140:141] op_sel_hi:[1,0] neg_lo:[0,1] neg_hi:[0,1]
	v_pk_mul_f32 v[100:101], v[100:101], v[100:101]
	v_fmac_f32_e32 v73, v94, v94
	v_mov_b32_e32 v102, v98
	v_mov_b32_e32 v103, v96
	v_add_f32_e32 v73, v101, v73
	v_pk_mul_f32 v[102:103], v[102:103], v[102:103]
	v_add_f32_e32 v73, v100, v73
	v_mov_b32_e32 v104, v99
	v_mov_b32_e32 v105, v97
	v_add_f32_e32 v73, v103, v73
	v_pk_mul_f32 v[104:105], v[104:105], v[104:105]
	v_add_f32_e32 v73, v102, v73
	v_add_f32_e32 v73, v105, v73
	v_add_f32_e32 v73, v104, v73
	s_add_u32 s68, s68, 0x40000
	s_addc_u32 s69, s69, 0
	v_add_f32_dpp v73, v73, v73 quad_perm:[1,0,3,2] row_mask:0xf bank_mask:0xf bound_ctrl:1
	v_add_u32_e32 v5, 0x100, v5
	v_add_u32_e32 v72, 64, v72
	v_add_f32_dpp v73, v73, v73 quad_perm:[2,3,0,1] row_mask:0xf bank_mask:0xf bound_ctrl:1
	s_cmp_lg_u32 s68, 0x80000
	v_lshlrev_b32_e32 v105, 16, v87
	v_add_f32_dpp v73, v73, v73 row_half_mirror row_mask:0xf bank_mask:0xf bound_ctrl:1
	v_fmamk_f32 v73, v73, 0x3c800000, v184
	v_rsq_f32_e32 v100, v73
	v_lshlrev_b32_e32 v104, 16, v86
	v_and_b32_e32 v87, 0xffff0000, v87
	v_and_b32_e32 v86, 0xffff0000, v86
	v_pk_mul_f32 v[92:93], v[92:93], v[100:101] op_sel_hi:[1,0]
	v_pk_mul_f32 v[94:95], v[94:95], v[100:101] op_sel_hi:[1,0]
	v_pk_mul_f32 v[96:97], v[96:97], v[100:101] op_sel_hi:[1,0]
	v_pk_mul_f32 v[98:99], v[98:99], v[100:101] op_sel_hi:[1,0]
	v_pk_fma_f32 v[92:93], v[66:67], v[92:93], v[62:63]
	v_pk_fma_f32 v[94:95], v[80:81], v[94:95], v[78:79]
	v_pk_fma_f32 v[96:97], v[70:71], v[96:97], v[74:75]
	v_pk_fma_f32 v[98:99], v[68:69], v[98:99], v[64:65]
	v_lshlrev_b32_e32 v101, 16, v85
	v_lshlrev_b32_e32 v100, 16, v84
	v_and_b32_e32 v85, 0xffff0000, v85
	v_and_b32_e32 v84, 0xffff0000, v84
	v_lshlrev_b32_e32 v103, 16, v89
	v_lshlrev_b32_e32 v102, 16, v88
	v_and_b32_e32 v89, 0xffff0000, v89
	v_and_b32_e32 v88, 0xffff0000, v88
	v_lshlrev_b32_e32 v107, 16, v91
	v_lshlrev_b32_e32 v106, 16, v90
	v_and_b32_e32 v91, 0xffff0000, v91
	v_and_b32_e32 v90, 0xffff0000, v90
	s_waitcnt lgkmcnt(0)
	v_pk_fma_f32 v[92:93], v[82:83], v[100:101], v[92:93] op_sel_hi:[0,1,1]
	v_pk_fma_f32 v[84:85], v[82:83], v[84:85], v[94:95] op_sel_hi:[0,1,1]
	v_pk_fma_f32 v[94:95], v[82:83], v[104:105], v[96:97] op_sel_hi:[0,1,1]
	v_pk_fma_f32 v[86:87], v[82:83], v[86:87], v[98:99] op_sel_hi:[0,1,1]
	v_pk_mul_f32 v[92:93], v[92:93], v[102:103]
	v_pk_mul_f32 v[84:85], v[84:85], v[88:89]
	v_pk_mul_f32 v[88:89], v[94:95], v[106:107]
	v_pk_mul_f32 v[86:87], v[86:87], v[90:91]
	v_cvt_pk_bf16_f32 v87, v89, v87
	v_cvt_pk_bf16_f32 v86, v88, v86
	v_cvt_pk_bf16_f32 v85, v93, v85
	v_cvt_pk_bf16_f32 v84, v92, v84
	global_store_dwordx4 v[76:77], v[84:87], off

.LBB0_1176:
	v_add_u32_e32 v74, s0, v178
	v_add_u32_e32 v5, s0, v179
	v_add_u32_e32 v78, s0, v177
	ds_read_b128 v[110:113], v74
	ds_read_b128 v[106:109], v78
	ds_read2st64_b64 v[154:157], v5 offset0:8 offset1:12
	ds_read2st64_b64 v[98:101], v5 offset0:9 offset1:13
	ds_read2st64_b64 v[114:117], v5 offset0:10 offset1:14
	ds_read2st64_b64 v[74:77], v5 offset0:11 offset1:15
	ds_read_b128 v[102:105], v78 offset:64
	ds_read_b128 v[94:97], v78 offset:128
	v_add_u32_e32 v5, s0, v176
	ds_read_b64_tr_b16 v[78:79], v5 offset:2048
	ds_read_b64_tr_b16 v[80:81], v5 offset:2560
	ds_read_b64_tr_b16 v[86:87], v5 offset:3072
	ds_read_b64_tr_b16 v[88:89], v5 offset:3584
	ds_read_b64_tr_b16 v[90:91], v5 offset:8704
	ds_read_b64_tr_b16 v[92:93], v5 offset:9216
	s_cmp_eq_u32 s0, 0x16880
	s_cbranch_scc1 .LBB0_1178
	ds_read_b64_tr_b16 v[148:149], v5 offset:13184
	ds_read_b64_tr_b16 v[150:151], v5 offset:13696
	ds_read_b64_tr_b16 v[142:143], v5 offset:14208
	ds_read_b64_tr_b16 v[144:145], v5 offset:14720
	ds_read_b64_tr_b16 v[140:141], v5 offset:21376
	v_add_u32_e32 v5, s0, v175
	ds_read_b64 v[146:147], v5
	v_mov_b32_e32 v152, 0
	v_mov_b32_e32 v153, 0
	s_branch .LBB0_1179

.LBB0_1179:
	v_cvt_pk_bf16_f32 v192, v6, v7
	v_cvt_pk_bf16_f32 v193, v8, v9
	v_cvt_pk_bf16_f32 v194, v10, v11
	v_cvt_pk_bf16_f32 v195, v12, v13
	v_cvt_pk_bf16_f32 v196, v14, v15
	v_cvt_pk_bf16_f32 v197, v16, v17
	v_cvt_pk_bf16_f32 v198, v18, v19
	v_cvt_pk_bf16_f32 v199, v20, v21
	s_waitcnt lgkmcnt(14)
	v_mfma_f32_16x16x32_bf16 v[62:65], v[62:65], v[192:195], 0
	v_mov_b32_e32 v5, v4
	s_waitcnt lgkmcnt(11)
	v_mfma_f32_16x16x32_bf16 v[66:69], v[66:69], v[196:199], 0
	s_waitcnt lgkmcnt(9)
	v_mfma_f32_16x16x32_bf16 v[70:73], v[70:73], v[2:5], 0
	s_waitcnt lgkmcnt(8)
	v_pk_add_f32 v[64:65], v[64:65], v[68:69]
	v_pk_add_f32 v[62:63], v[62:63], v[66:67]
	v_pk_add_f32 v[64:65], v[64:65], v[72:73]
	v_pk_add_f32 v[62:63], v[62:63], v[70:71]
	v_pk_mul_f32 v[8:9], v[8:9], v[112:113]
	v_cvt_pk_bf16_f32 v62, v62, v63
	v_cvt_pk_bf16_f32 v63, v64, v65
	v_mov_b32_e32 v64, v2
	v_mov_b32_e32 v65, v3
	v_pk_mul_f32 v[6:7], v[6:7], v[110:111]
	v_pk_mul_f32 v[12:13], v[12:13], v[108:109]
	v_pk_mul_f32 v[10:11], v[10:11], v[106:107]
	s_waitcnt lgkmcnt(7)
	v_pk_mul_f32 v[16:17], v[16:17], v[104:105]
	v_pk_mul_f32 v[14:15], v[14:15], v[102:103]
	s_waitcnt lgkmcnt(6)
	v_pk_mul_f32 v[20:21], v[20:21], v[96:97]
	v_pk_mul_f32 v[18:19], v[18:19], v[94:95]
	s_waitcnt lgkmcnt(4)
	v_mfma_f32_16x16x32_bf16 v[66:69], v[78:81], v[192:195], 0
	s_addk_i32 s0, 0x3380
	s_cmp_eq_u32 s0, 0x19c00
	s_waitcnt lgkmcnt(2)
	v_mfma_f32_16x16x32_bf16 v[70:73], v[86:89], v[196:199], 0
	v_mfma_f32_16x16x32_bf16 v[6:9], v[154:157], v[62:65], v[6:9]
	v_mfma_f32_16x16x32_bf16 v[10:13], v[98:101], v[62:65], v[10:13]
	s_nop 5
	v_add_f32_e64 v2, v68, v72
	v_add_f32_e64 v3, v69, v73
	v_pk_add_f32 v[66:67], v[66:67], v[70:71]
	v_mfma_f32_16x16x32_bf16 v[14:17], v[114:117], v[62:65], v[14:17]
	v_mfma_f32_16x16x32_bf16 v[18:21], v[74:77], v[62:65], v[18:21]
	s_waitcnt lgkmcnt(0)
	v_mfma_f32_16x16x32_bf16 v[62:65], v[90:93], v[62:65], 0
	s_nop 7
	v_pk_add_f32 v[2:3], v[2:3], v[64:65]
	v_pk_add_f32 v[62:63], v[66:67], v[62:63]
	s_nop 0
	v_cvt_pk_bf16_f32 v62, v62, v63
	v_cvt_pk_bf16_f32 v63, v2, v3
	ds_write_b64 v133, v[62:63]
	v_add_u32_e32 v133, 32, v133
	s_cbranch_scc1 .LBB0_1154
	v_mov_b64_e32 v[2:3], v[146:147]
	v_mov_b32_e32 v62, v148
	v_mov_b32_e32 v63, v149
	v_mov_b32_e32 v64, v150
	v_mov_b32_e32 v65, v151
	v_mov_b32_e32 v66, v142
	v_mov_b32_e32 v67, v143
	v_mov_b32_e32 v68, v144
	v_mov_b32_e32 v69, v145
	v_mov_b32_e32 v70, v140
	v_mov_b32_e32 v71, v141
	v_mov_b32_e32 v72, v152
	v_mov_b32_e32 v73, v153
	s_branch .LBB0_1176

.LBB0_1183:
	v_add_u32_e32 v33, s0, v5
	v_add_u32_e32 v32, 0x800, v33
	s_waitcnt vmcnt(4)
	v_add_u32_e32 v43, 0, v40
	v_add_u32_e32 v42, 0x820, v33
	v_ashrrev_i32_e32 v33, 31, v32
	v_lshlrev_b32_e32 v41, 1, v124
	v_add_u32_e32 v36, 0, v37
	s_waitcnt vmcnt(2)
	v_add_u32_e32 v52, 0x22000, v43
	s_waitcnt vmcnt(0)
	v_add_u32_e32 v60, 0x22080, v43
	v_ashrrev_i32_e32 v43, 31, v42
	v_lshlrev_b64 v[32:33], 12, v[32:33]
	v_add_u32_e32 v44, 0x1dc00, v36
	v_add_u32_e32 v45, 0x1dd00, v36
	v_add_u32_e32 v46, 0x1de00, v36
	v_add_u32_e32 v47, 0x1df00, v36
	v_add_u32_e32 v51, 0x1e300, v36
	v_lshlrev_b64 v[42:43], 12, v[42:43]
	v_or_b32_e32 v32, v32, v41
	v_add_u32_e32 v48, 0x1e000, v36
	v_add_u32_e32 v49, 0x1e100, v36
	v_add_u32_e32 v50, 0x1e200, v36
	v_add_u32_e32 v53, 0x1dc40, v36
	v_add_u32_e32 v54, 0x1dd40, v36
	v_add_u32_e32 v55, 0x1de40, v36
	v_add_u32_e32 v56, 0x1df40, v36
	v_add_u32_e32 v57, 0x1e040, v36
	v_add_u32_e32 v58, 0x1e140, v36
	v_add_u32_e32 v59, 0x1e240, v36
	v_add_u32_e32 v36, 0x1e340, v36
	ds_read_u16 v61, v44
	ds_read_u16 v62, v46
	ds_read_u16 v63, v47
	ds_read_u16 v64, v48
	ds_read_u16 v65, v50
	ds_read_u16 v51, v51
	ds_read_u16 v66, v49
	ds_read_u16 v67, v45
	v_or_b32_e32 v42, v42, v41
	v_lshl_add_u64 v[46:47], s[2:3], 0, v[32:33]
	v_lshl_add_u64 v[44:45], s[4:5], 0, v[32:33]
	ds_read_b32 v50, v52
	ds_read_u16 v68, v53
	ds_read_u16 v69, v55
	ds_read_u16 v70, v56
	ds_read_u16 v72, v57
	ds_read_u16 v71, v59
	ds_read_u16 v74, v58
	ds_read_u16 v73, v54
	ds_read_u16 v75, v36
	ds_read_b32 v36, v60
	v_lshl_add_u64 v[52:53], s[6:7], 0, v[32:33]
	v_lshl_add_u64 v[54:55], s[2:3], 0, v[42:43]
	v_lshl_add_u64 v[56:57], s[4:5], 0, v[42:43]
	v_lshl_add_u64 v[32:33], s[6:7], 0, v[42:43]
	global_load_dwordx4 v[42:45], v[44:45], off
	s_nop 0
	global_load_dwordx4 v[46:49], v[46:47], off
	s_waitcnt lgkmcnt(14)
	v_lshlrev_b32_e32 v58, 16, v61
	s_waitcnt lgkmcnt(10)
	v_lshlrev_b32_e32 v60, 16, v67
	v_add_f32_e32 v41, 0, v58
	v_lshlrev_b32_e32 v59, 16, v62
	v_add_f32_e32 v41, v41, v60
	v_lshlrev_b32_e32 v61, 16, v63
	v_add_f32_e32 v41, v41, v59
	v_lshlrev_b32_e32 v62, 16, v64
	v_add_f32_e32 v41, v41, v61
	v_lshlrev_b32_e32 v64, 16, v66
	v_add_f32_e32 v41, v41, v62
	v_lshlrev_b32_e32 v63, 16, v65
	v_add_f32_e32 v41, v41, v64
	v_lshlrev_b32_e32 v65, 16, v51
	v_add_f32_e32 v41, v41, v63
	v_add_f32_e32 v41, v41, v65
	s_waitcnt lgkmcnt(7)
	v_lshlrev_b32_e32 v67, 16, v69
	s_waitcnt lgkmcnt(6)
	v_lshlrev_b32_e32 v69, 16, v70
	v_add_f32_dpp v41, v41, v41 quad_perm:[1,0,3,2] row_mask:0xf bank_mask:0xf bound_ctrl:1
	s_waitcnt lgkmcnt(5)
	v_lshlrev_b32_e32 v70, 16, v72
	s_waitcnt lgkmcnt(3)
	v_lshlrev_b32_e32 v72, 16, v74
	v_add_f32_dpp v41, v41, v41 quad_perm:[2,3,0,1] row_mask:0xf bank_mask:0xf bound_ctrl:1
	v_lshlrev_b32_e32 v66, 16, v68
	s_waitcnt lgkmcnt(2)
	v_lshlrev_b32_e32 v68, 16, v73
	v_add_f32_dpp v41, v41, v41 row_half_mirror row_mask:0xf bank_mask:0xf bound_ctrl:1
	v_mul_f32_e32 v74, 0x3c800000, v41
	s_waitcnt lgkmcnt(1)
	v_pk_add_f32 v[58:59], v[58:59], v[74:75] op_sel_hi:[1,0] neg_lo:[0,1] neg_hi:[0,1]
	v_pk_add_f32 v[60:61], v[60:61], v[74:75] op_sel_hi:[1,0] neg_lo:[0,1] neg_hi:[0,1]
	v_lshlrev_b32_e32 v73, 16, v75
	v_pk_add_f32 v[62:63], v[62:63], v[74:75] op_sel_hi:[1,0] neg_lo:[0,1] neg_hi:[0,1]
	v_pk_add_f32 v[64:65], v[64:65], v[74:75] op_sel_hi:[1,0] neg_lo:[0,1] neg_hi:[0,1]
	v_mov_b32_e32 v74, v61
	v_mov_b32_e32 v75, v59
	v_mul_f32_e32 v41, v58, v58
	v_pk_mul_f32 v[74:75], v[74:75], v[74:75]
	v_fmac_f32_e32 v41, v60, v60
	v_mov_b32_e32 v78, v64
	v_mov_b32_e32 v79, v62
	v_add_f32_e32 v41, v75, v41
	v_pk_mul_f32 v[78:79], v[78:79], v[78:79]
	v_add_f32_e32 v41, v74, v41
	v_mov_b32_e32 v80, v65
	v_mov_b32_e32 v81, v63
	v_add_f32_e32 v41, v79, v41
	v_pk_mul_f32 v[80:81], v[80:81], v[80:81]
	v_add_f32_e32 v41, v78, v41
	v_add_f32_e32 v41, v81, v41
	v_add_f32_e32 v51, 0, v66
	v_add_f32_e32 v41, v80, v41
	v_add_f32_e32 v51, v51, v68
	v_add_f32_e32 v51, v51, v67
	v_add_f32_dpp v41, v41, v41 quad_perm:[1,0,3,2] row_mask:0xf bank_mask:0xf bound_ctrl:1
	v_add_f32_e32 v51, v51, v69
	v_add_f32_e32 v51, v51, v70
	v_add_f32_dpp v41, v41, v41 quad_perm:[2,3,0,1] row_mask:0xf bank_mask:0xf bound_ctrl:1
	v_lshlrev_b32_e32 v71, 16, v71
	v_add_f32_e32 v51, v51, v72
	v_add_f32_dpp v41, v41, v41 row_half_mirror row_mask:0xf bank_mask:0xf bound_ctrl:1
	v_fmamk_f32 v41, v41, 0x3c800000, v184
	v_rsq_f32_e32 v74, v41
	v_add_f32_e32 v51, v51, v71
	v_add_f32_e32 v51, v51, v73
	v_add_u32_e32 v37, 0x80, v37
	v_pk_mul_f32 v[58:59], v[58:59], v[74:75] op_sel_hi:[1,0]
	v_add_f32_dpp v51, v51, v51 quad_perm:[1,0,3,2] row_mask:0xf bank_mask:0xf bound_ctrl:1
	v_pk_mul_f32 v[60:61], v[60:61], v[74:75] op_sel_hi:[1,0]
	v_pk_mul_f32 v[62:63], v[62:63], v[74:75] op_sel_hi:[1,0]
	v_add_f32_dpp v51, v51, v51 quad_perm:[2,3,0,1] row_mask:0xf bank_mask:0xf bound_ctrl:1
	v_pk_mul_f32 v[64:65], v[64:65], v[74:75] op_sel_hi:[1,0]
	v_pk_fma_f32 v[58:59], v[26:27], v[58:59], v[22:23]
	v_add_f32_dpp v51, v51, v51 row_half_mirror row_mask:0xf bank_mask:0xf bound_ctrl:1
	v_pk_fma_f32 v[60:61], v[38:39], v[60:61], v[2:3]
	v_pk_fma_f32 v[62:63], v[30:31], v[62:63], v[34:35]
	v_pk_fma_f32 v[64:65], v[28:29], v[64:65], v[24:25]
	v_mul_f32_e32 v76, 0x3c800000, v51
	s_add_i32 s0, s0, 64
	v_add_u32_e32 v40, 0x100, v40
	s_cmp_lg_u32 s0, 0
	s_waitcnt vmcnt(1)
	v_lshlrev_b32_e32 v75, 16, v43
	v_lshlrev_b32_e32 v74, 16, v42
	v_and_b32_e32 v43, 0xffff0000, v43
	v_and_b32_e32 v42, 0xffff0000, v42
	v_lshlrev_b32_e32 v81, 16, v45
	v_lshlrev_b32_e32 v80, 16, v44
	v_and_b32_e32 v45, 0xffff0000, v45
	v_and_b32_e32 v44, 0xffff0000, v44
	s_waitcnt vmcnt(0)
	v_lshlrev_b32_e32 v79, 16, v47
	v_lshlrev_b32_e32 v78, 16, v46
	v_and_b32_e32 v47, 0xffff0000, v47
	v_and_b32_e32 v46, 0xffff0000, v46
	v_lshlrev_b32_e32 v83, 16, v49
	v_lshlrev_b32_e32 v82, 16, v48
	v_and_b32_e32 v49, 0xffff0000, v49
	v_and_b32_e32 v48, 0xffff0000, v48
	v_pk_fma_f32 v[58:59], v[50:51], v[74:75], v[58:59] op_sel_hi:[0,1,1]
	v_pk_fma_f32 v[42:43], v[50:51], v[42:43], v[60:61] op_sel_hi:[0,1,1]
	v_pk_fma_f32 v[60:61], v[50:51], v[80:81], v[62:63] op_sel_hi:[0,1,1]
	v_pk_fma_f32 v[44:45], v[50:51], v[44:45], v[64:65] op_sel_hi:[0,1,1]
	v_pk_mul_f32 v[50:51], v[58:59], v[78:79]
	v_pk_mul_f32 v[42:43], v[42:43], v[46:47]
	v_pk_mul_f32 v[46:47], v[60:61], v[82:83]
	v_pk_mul_f32 v[44:45], v[44:45], v[48:49]
	v_cvt_pk_bf16_f32 v45, v47, v45
	v_cvt_pk_bf16_f32 v44, v46, v44
	v_cvt_pk_bf16_f32 v43, v51, v43
	v_cvt_pk_bf16_f32 v42, v50, v42
	global_store_dwordx4 v[52:53], v[42:45], off
	global_load_dwordx4 v[42:45], v[56:57], off
	s_nop 0
	global_load_dwordx4 v[46:49], v[54:55], off
	v_pk_add_f32 v[50:51], v[66:67], v[76:77] op_sel_hi:[1,0] neg_lo:[0,1] neg_hi:[0,1]
	v_pk_add_f32 v[52:53], v[68:69], v[76:77] op_sel_hi:[1,0] neg_lo:[0,1] neg_hi:[0,1]
	v_mov_b32_e32 v59, v51
	v_mov_b32_e32 v58, v53
	v_mul_f32_e32 v41, v50, v50
	v_pk_add_f32 v[54:55], v[70:71], v[76:77] op_sel_hi:[1,0] neg_lo:[0,1] neg_hi:[0,1]
	v_pk_add_f32 v[56:57], v[72:73], v[76:77] op_sel_hi:[1,0] neg_lo:[0,1] neg_hi:[0,1]
	v_pk_mul_f32 v[58:59], v[58:59], v[58:59]
	v_fmac_f32_e32 v41, v52, v52
	v_mov_b32_e32 v60, v56
	v_mov_b32_e32 v61, v54
	v_add_f32_e32 v41, v59, v41
	v_pk_mul_f32 v[60:61], v[60:61], v[60:61]
	v_add_f32_e32 v41, v58, v41
	v_mov_b32_e32 v62, v57
	v_mov_b32_e32 v63, v55
	v_add_f32_e32 v41, v61, v41
	v_pk_mul_f32 v[62:63], v[62:63], v[62:63]
	v_add_f32_e32 v41, v60, v41
	v_add_f32_e32 v41, v63, v41
	v_add_f32_e32 v41, v62, v41
	s_waitcnt vmcnt(1)
	v_lshlrev_b32_e32 v63, 16, v45
	v_add_f32_dpp v41, v41, v41 quad_perm:[1,0,3,2] row_mask:0xf bank_mask:0xf bound_ctrl:1
	v_lshlrev_b32_e32 v62, 16, v44
	v_and_b32_e32 v45, 0xffff0000, v45
	v_add_f32_dpp v41, v41, v41 quad_perm:[2,3,0,1] row_mask:0xf bank_mask:0xf bound_ctrl:1
	v_and_b32_e32 v44, 0xffff0000, v44
	s_waitcnt vmcnt(0)
	v_lshlrev_b32_e32 v61, 16, v47
	v_add_f32_dpp v41, v41, v41 row_half_mirror row_mask:0xf bank_mask:0xf bound_ctrl:1
	v_fmamk_f32 v41, v41, 0x3c800000, v184
	v_rsq_f32_e32 v58, v41
	v_lshlrev_b32_e32 v60, 16, v46
	v_and_b32_e32 v47, 0xffff0000, v47
	v_and_b32_e32 v46, 0xffff0000, v46
	v_pk_mul_f32 v[50:51], v[50:51], v[58:59] op_sel_hi:[1,0]
	v_pk_mul_f32 v[52:53], v[52:53], v[58:59] op_sel_hi:[1,0]
	v_pk_mul_f32 v[54:55], v[54:55], v[58:59] op_sel_hi:[1,0]
	v_pk_mul_f32 v[56:57], v[56:57], v[58:59] op_sel_hi:[1,0]
	v_pk_fma_f32 v[50:51], v[26:27], v[50:51], v[22:23]
	v_pk_fma_f32 v[52:53], v[38:39], v[52:53], v[2:3]
	v_pk_fma_f32 v[54:55], v[30:31], v[54:55], v[34:35]
	v_pk_fma_f32 v[56:57], v[28:29], v[56:57], v[24:25]
	v_lshlrev_b32_e32 v59, 16, v43
	v_lshlrev_b32_e32 v58, 16, v42
	v_and_b32_e32 v43, 0xffff0000, v43
	v_and_b32_e32 v42, 0xffff0000, v42
	v_lshlrev_b32_e32 v65, 16, v49
	v_lshlrev_b32_e32 v64, 16, v48
	v_and_b32_e32 v49, 0xffff0000, v49
	v_and_b32_e32 v48, 0xffff0000, v48
	s_waitcnt lgkmcnt(0)
	v_pk_fma_f32 v[50:51], v[36:37], v[58:59], v[50:51] op_sel_hi:[0,1,1]
	v_pk_fma_f32 v[42:43], v[36:37], v[42:43], v[52:53] op_sel_hi:[0,1,1]
	v_pk_fma_f32 v[52:53], v[36:37], v[62:63], v[54:55] op_sel_hi:[0,1,1]
	v_pk_fma_f32 v[44:45], v[36:37], v[44:45], v[56:57] op_sel_hi:[0,1,1]
	v_pk_mul_f32 v[50:51], v[50:51], v[60:61]
	v_pk_mul_f32 v[42:43], v[42:43], v[46:47]
	v_pk_mul_f32 v[46:47], v[52:53], v[64:65]
	v_pk_mul_f32 v[44:45], v[44:45], v[48:49]
	v_cvt_pk_bf16_f32 v45, v47, v45
	v_cvt_pk_bf16_f32 v44, v46, v44
	v_cvt_pk_bf16_f32 v43, v51, v43
	v_cvt_pk_bf16_f32 v42, v50, v42
	global_store_dwordx4 v[32:33], v[42:45], off
	s_cbranch_scc1 .LBB0_1183
